# P2 pass-1 rebalance: sample-path workgroups take one cached-attention unit each, workgroups 64-95 take the other 32 after their GLA chain<0> item (same work, shorter barrier pole); plus batched fold
# speedup vs baseline: 1.0129x; 1.0025x over previous
; #define cK karg(2)
; #define cV karg(3)
; #define cF karg(4)
; #define S0 karg(5)
; __global__ void __launch_bounds__(512, 2) fwd_kernel(Args args) {
;     ...
;             for (int it = bx; it < 224; it += G) gla::chain<0>((it & 31) >> 2, it & 3, it >> 5, (float*)(ws + WS_SLOC), (float*)(ws + WS_DTOT), QB, KB, VB, OBG, RB, A1, w_a2, b_a2, g_gla, out + O_SP, (char*)lds, wave);
;             if (bx >= 224 || G < 256) {
;                 const int nb = G < 256 ? G : G - 224, b0 = G < 256 ? bx : bx - 224;
;                 if (mixm & 4) { for (int u = b0; u < 64; u += nb) sattn::unit(u >> 3, u & 7, QA, OA, cK, cV, cF, out, (char*)lds, wave); }
;                 if (mixm & 8) { for (int u = b0; u < 32; u += nb) gla::sample_unit(u >> 2, u & 3, QB, KB, VB, OBG, RB, A1, w_a2, b_a2, g_gla, S0, out + O_SS, (char*)lds, wave); } }
.LBB0_494:
	s_cmpk_gt_i32 s2, 0xdf
	s_cselect_b64 s[6:7], -1, 0
	s_cmpk_lt_i32 s88, 0x100
	s_cselect_b64 s[4:5], -1, 0
	v_readlane_b32 s74, v246, 27
	s_or_b64 s[6:7], s[6:7], s[4:5]
	s_sub_i32 s8, s2, 64
	s_cmp_lt_u32 s8, 32
	s_cselect_b64 s[8:9], -1, 0
	s_or_b64 s[6:7], s[6:7], s[8:9]
	s_lshl_b32 s8, s74, 2
	s_add_i32 s30, s8, 0x100
	s_and_b64 vcc, exec, s[6:7]
	v_readlane_b32 s75, v246, 28
	v_writelane_b32 v245, s30, 59
	s_cbranch_vccz .LBB0_598
	s_add_i32 s8, s88, 0xffffff20
	s_and_b64 s[6:7], s[4:5], exec
	s_cselect_b32 s78, s88, 64
	s_add_i32 s6, s2, 0xffffff20
	s_sub_i32 s7, s2, 32
	s_sub_i32 s9, s2, 64
	s_cmp_lt_u32 s9, 32
	s_cselect_b32 s6, s7, s6
	s_and_b64 s[4:5], s[4:5], exec
	s_cselect_b32 s8, s2, s6
	s_cmp_gt_i32 s8, 63
	s_cbranch_scc1 .LBB0_555
	v_readlane_b32 s4, v246, 14
	s_cmpk_gt_u32 s4, 0x103f
	v_readlane_b32 s4, v246, 4
	s_mov_b32 s6, s4
	s_mulk_i32 s4, 0x107c
	v_mbcnt_lo_u32_b32 v1, -1, 0
	s_cselect_b64 s[34:35], -1, 0
	s_add_i32 s9, s10, s4
	s_lshl_b32 s4, s6, 7
	v_mbcnt_hi_u32_b32 v33, -1, v1
	s_add_i32 s29, s6, -8
	s_add_i32 s31, s4, 0x100
	s_mov_b32 s93, 0
	s_movk_i32 s21, 0x810
	v_mov_b32_e32 v31, 0
	v_and_b32_e32 v35, 64, v33
	v_add_u32_e32 v41, -1, v33
	v_add_u32_e32 v44, -2, v33
	v_add_u32_e32 v45, -4, v33
	v_add_u32_e32 v46, -8, v33
	s_mov_b32 s36, 0xbfb8aa3b
	s_mov_b32 s22, 0xf149f2ca
	s_mov_b32 s23, 0xefa18f08
	s_mov_b32 s24, 0xc2fc0000
	v_add_u32_e32 v47, -16, v33
	v_mov_b32_e32 v48, 0x100
	v_mov_b32_e32 v49, 0xf149f2ca
	v_mov_b32_e32 v50, 0x42800000
	v_not_b32_e32 v51, 63
	s_mov_b32 s25, s8
	v_readlane_b32 s5, v246, 5
	s_branch .LBB0_498
